# forget-gate scans: four per workgroup (one per SIMD) on workgroups 0..31, instead of one per workgroup on 128
# baseline (speedup 1.0000x reference)
.LBB0_581:
	s_or_b64 exec, exec, s[12:13]
	v_readlane_b32 s2, v252, 4
	v_lshrrev_b32_e32 v0, 6, v26
	v_mov_b32_e32 v1, 0x80
	s_nop 1
	s_lshr_b32 s2, s2, 1
	v_cmp_gt_u32_e32 vcc, 4, v0
	v_add_u32_e32 v0, s2, v0
	v_mov_b32_e32 v65, 0
	v_cndmask_b32_e32 v64, v1, v0, vcc
	s_movk_i32 s2, 0x80
	v_cmp_gt_i32_e32 vcc, s2, v64
	s_and_saveexec_b64 s[16:17], vcc
	s_cbranch_execz .LBB0_584
	s_load_dwordx2 s[2:3], s[6:7], 0x58
	v_and_b32_e32 v2, 7, v64
	v_lshlrev_b32_e32 v0, 2, v2
	v_mov_b32_e32 v1, 0
	v_mbcnt_hi_u32_b32 v4, -1, v220
	s_waitcnt lgkmcnt(0)
	v_lshl_add_u64 v[66:67], s[2:3], 0, v[0:1]
	v_lshlrev_b32_e32 v0, 18, v2
	v_lshl_add_u64 v[2:3], s[0:1], 0, v[0:1]
	v_lshlrev_b32_e32 v0, 8, v19
	v_lshl_add_u64 v[0:1], v[2:3], 0, v[0:1]
	s_mov_b64 s[2:3], 0x3aa0000
	v_and_b32_e32 v5, 64, v4
	v_lshl_add_u64 v[68:69], v[0:1], 0, s[2:3]
	v_add_u32_e32 v0, -1, v4
	v_cmp_lt_i32_e32 vcc, v0, v5
	s_ashr_i32 s95, s94, 31
	s_lshl_b64 s[18:19], s[94:95], 14
	v_cndmask_b32_e32 v0, v0, v4, vcc
	v_lshlrev_b32_e32 v78, 2, v0
	v_add_u32_e32 v0, -2, v4
	v_cmp_lt_i32_e64 s[4:5], v0, v5
	v_cmp_eq_u32_e32 vcc, 0, v19
	v_readlane_b32 s87, v252, 5
	v_cndmask_b32_e64 v0, v0, v4, s[4:5]
	v_lshlrev_b32_e32 v79, 2, v0
	v_add_u32_e32 v0, -4, v4
	v_cmp_lt_i32_e64 s[6:7], v0, v5
	v_cmp_gt_u32_e64 s[4:5], 2, v19
	s_mov_b64 s[20:21], 0
	v_cndmask_b32_e64 v0, v0, v4, s[6:7]
	v_lshlrev_b32_e32 v80, 2, v0
	v_add_u32_e32 v0, -8, v4
	v_cmp_lt_i32_e64 s[8:9], v0, v5
	v_cmp_gt_u32_e64 s[6:7], 4, v19
	s_mov_b32 s23, 0x42ce8ed0
	v_cndmask_b32_e64 v0, v0, v4, s[8:9]
	v_lshlrev_b32_e32 v81, 2, v0
	v_add_u32_e32 v0, -16, v4
	v_cmp_lt_i32_e64 s[10:11], v0, v5
	v_cmp_gt_u32_e64 s[8:9], 8, v19
	s_mov_b32 s24, 0xc2b17218
	v_cndmask_b32_e64 v0, v0, v4, s[10:11]
	v_lshlrev_b32_e32 v82, 2, v0
	v_subrev_u32_e32 v0, 32, v4
	v_cmp_lt_i32_e64 s[12:13], v0, v5
	v_cmp_gt_u32_e64 s[10:11], 16, v19
	s_mov_b32 s25, 0x7f800000
	v_cndmask_b32_e64 v0, v0, v4, s[12:13]
	v_lshlrev_b32_e32 v83, 2, v0
	v_lshlrev_b64 v[0:1], 14, v[64:65]
	v_lshl_or_b32 v0, v19, 8, v0
	v_lshl_add_u64 v[0:1], s[0:1], 0, v[0:1]
	s_mov_b64 s[0:1], 0x30a00f0
	v_cmp_gt_u32_e64 s[12:13], 32, v19
	v_lshl_add_u64 v[70:71], v[0:1], 0, s[0:1]
	s_mov_b32 s0, 0xbfb8aa3b
	s_mov_b32 s1, 0xb2a5705f
	v_mov_b32_e32 v65, 0x7f800000
	s_mov_b32 s26, 0x3f2aaaab
	v_mov_b32_e32 v84, 0x3ecc95a3
	s_mov_b32 s27, 0x3f317218
	s_mov_b32 s28, 0x33800000
	s_mov_b32 s22, 0x3fb8aa3b
	s_movk_i32 s29, 0x7f
	v_mov_b32_e32 v72, 0x3f317218
